# v5 + spatial phase: norm-gain loads issued ahead of next-unit prefetch, counted vmcnt at the tile-write and loop top (no full drains)
# baseline (speedup 1.0000x reference)
; __device__ __forceinline__ void phase_spatial(const Args& A, int j, LAS unsigned char* lds, int tid, int wid, int lane, bf16* ydst, unsigned ystride) {
;     ...
;     const f32x2* statv = (const f32x2*)(A.ws + WS_STATV);
;     const bf16* GVT = (const bf16*)(A.ws + WS_GVT);
;     const bf16* UZ = (const bf16*)(A.ws + WS_UZ);
;     const float* ng = A.in[I_SNG] + (size_t)j * EW;
;     const int r32 = lane & 31, half = lane >> 5;
;     f32x2 stv[8]; f32x4 wv[8];
;     ...
;     if ((int)blockIdx.x < (MTOK / SBLK) * NG) SP_PREFETCH((int)blockIdx.x);
;     for (int unit = blockIdx.x; unit < (MTOK / SBLK) * NG; unit += gridDim.x) {
;         const int g = unit & 15, nblk = unit >> 4, t0 = nblk * SBLK;
; __global__ void __launch_bounds__(NTHREADS, 2) fwd_kernel(Args A_) {
;     ...
;                 } else if (k == 1) { if (PHMASK & 16) {
;     ...
;                     if (li == 0) { phase_spatial(A, j, lds, tid, wid, lane, (bf16*)A.out, EW); xcd_barrier(xbar, wid0 == 0); }
;     ...
;                     phase_spatial(A, j, lds, tid, wid, lane, (bf16*)(ws + WS_UZ), EW); } }
.LBB0_314:
	s_cmp_eq_u32 s58, 1
	s_mov_b64 s[0:1], -1
	s_cbranch_scc0 .LBB0_325
	v_readlane_b32 s0, v250, 54
	v_readlane_b32 s1, v250, 55
	s_mov_b64 s[28:29], s[12:13]
	s_andn2_b64 vcc, exec, s[0:1]
	s_cbranch_vccnz .LBB0_324
	s_add_u32 s6, s14, 0xf400000
	s_addc_u32 s7, s15, 0
	s_add_u32 s16, s14, 0x2f400000
	s_addc_u32 s17, s15, 0
	s_lshr_b32 s19, s59, 1
	s_mov_b32 s2, s52
	s_mov_b32 s1, s57
	s_mov_b32 s3, s59
	s_mov_b32 s4, s58
	s_mov_b64 s[8:9], s[60:61]
	v_readlane_b32 s52, v249, 19
	s_lshl_b32 s0, s19, 14
	v_readlane_b32 s60, v249, 27
	v_readlane_b32 s61, v249, 28
	v_readlane_b32 s66, v249, 33
	v_readlane_b32 s67, v249, 34
	s_mov_b64 s[60:61], s[8:9]
	s_add_u32 s8, s66, s0
	s_addc_u32 s9, s67, 0
	v_readlane_b32 s57, v249, 24
	s_add_u32 s12, s14, 0x100000
	s_mov_b32 s57, s1
	s_addc_u32 s13, s15, 0
	v_readlane_b32 s0, v250, 22
	v_readlane_b32 s1, v250, 23
	s_add_u32 s0, s12, s0
	v_lshlrev_b32_e32 v0, 3, v196
	s_addc_u32 s1, s13, s1
	s_waitcnt vmcnt(0) lgkmcnt(0)
	v_lshlrev_b64 v[2:3], 3, v[0:1]
	v_lshl_add_u64 v[4:5], s[0:1], 0, v[2:3]
	s_lshl_b32 s0, s19, 20
	v_readlane_b32 s59, v249, 26
	s_mov_b32 s52, s2
	s_add_u32 s2, s36, s0
	s_mov_b32 s59, s3
	s_addc_u32 s3, s37, 0
	v_readlane_b32 s0, v250, 61
	flat_load_dwordx4 v[66:69], v[4:5]
	flat_load_dwordx4 v[70:73], v[4:5] offset:16
	flat_load_dwordx4 v[74:77], v[4:5] offset:32
	flat_load_dwordx4 v[78:81], v[4:5] offset:48
	s_add_u32 s0, s2, s0
	v_lshlrev_b32_e32 v4, 5, v196
	v_mov_b32_e32 v5, v1
	s_addc_u32 s1, s3, 0
	v_lshlrev_b64 v[4:5], 2, v[4:5]
	v_lshl_add_u64 v[6:7], s[0:1], 0, v[4:5]
	global_load_dwordx4 v[82:85], v[6:7], off offset:48
	global_load_dwordx4 v[86:89], v[6:7], off offset:32
	global_load_dwordx4 v[90:93], v[6:7], off offset:16
	global_load_dwordx4 v[94:97], v[6:7], off
	global_load_dwordx4 v[98:101], v[6:7], off offset:112
	global_load_dwordx4 v[102:105], v[6:7], off offset:96
	global_load_dwordx4 v[106:109], v[6:7], off offset:80
	global_load_dwordx4 v[110:113], v[6:7], off offset:64
	v_ashrrev_i32_e32 v8, 5, v194
	v_and_b32_e32 v197, 0xf8, v0
	v_and_b32_e32 v0, 3, v194
	v_and_b32_e32 v10, -4, v196
	v_readlane_b32 s20, v249, 3
	v_lshlrev_b32_e32 v12, 7, v0
	v_lshl_add_u64 v[178:179], s[12:13], 0, v[2:3]
	v_lshlrev_b32_e32 v2, 2, v8
	v_ashrrev_i32_e32 v6, 2, v196
	v_add_u32_e32 v212, s20, v10
	v_add_u32_e32 v213, s20, v12
	s_movk_i32 s20, 0x110
	v_ashrrev_i32_e32 v3, 31, v2
	v_readlane_b32 s21, v249, 2
	v_mul_lo_u32 v7, v6, s20
	v_readlane_b32 s20, v249, 4
	v_readlane_b32 s22, v249, 5
	v_lshl_add_u64 v[180:181], v[2:3], 2, s[8:9]
	s_lshl_b32 s8, s57, 7
	v_add_u32_e32 v211, s21, v10
	v_add_u32_e32 v214, s20, v10
	v_add_u32_e32 v215, s22, v10
	v_lshlrev_b32_e32 v10, 4, v8
	s_add_i32 s8, s8, 0
	v_and_b32_e32 v195, 31, v194
	v_readlane_b32 s58, v249, 25
	v_ashrrev_i32_e32 v9, 5, v196
	v_lshlrev_b32_e32 v11, 5, v0
	v_add_u32_e32 v2, s8, v10
	s_movk_i32 s8, 0x410
	s_mov_b32 s58, s4
	v_lshlrev_b32_e32 v174, 12, v9
	v_lshlrev_b32_e32 v176, 3, v8
	v_cmp_gt_i32_e32 vcc, 64, v6
	v_cmp_lt_u32_e64 s[4:5], 1, v0
	v_mul_lo_u32 v217, v9, s8
	v_or_b32_e32 v3, 8, v11
	v_or_b32_e32 v8, 16, v11
	v_or_b32_e32 v9, 24, v11
	v_lshlrev_b32_e32 v11, 2, v195
	s_lshl_b32 s18, s57, 5
	s_and_b64 s[4:5], vcc, s[4:5]
	s_lshl_b32 s19, s19, 13
	v_add_u32_e32 v218, s21, v12
	v_or_b32_e32 v12, 0x80, v11
	v_readlane_b32 s54, v249, 21
	v_readlane_b32 s55, v249, 22
	v_add_u32_e32 v222, s20, v11
	v_add_u32_e32 v223, s22, v11
	v_add_u32_e32 v224, s20, v12
	v_add_u32_e32 v225, s22, v12
	v_or_b32_e32 v12, 0x100, v11
	v_or_b32_e32 v11, 0x180, v11
	v_lshl_add_u64 v[200:201], s[2:3], 0, v[4:5]
	s_add_u32 s2, s38, s19
	v_readlane_b32 s53, v249, 20
	v_readlane_b32 s54, v249, 59
	v_cmp_eq_u32_e64 s[0:1], 0, v0
	v_add_u32_e32 v13, 0, v7
	v_ashrrev_i32_e32 v7, 31, v6
	v_add_u32_e32 v14, 0, v10
	v_lshl_add_u32 v216, v197, 2, 0
	v_lshlrev_b32_e32 v0, 6, v0
	v_lshl_add_u32 v219, v3, 2, s21
	v_lshlrev_b32_e32 v3, 1, v3
	v_lshl_add_u32 v220, v8, 2, s21
	v_lshlrev_b32_e32 v8, 1, v8
	v_lshl_add_u32 v221, v9, 2, s21
	v_lshlrev_b32_e32 v9, 1, v9
	v_mul_u32_u24_e32 v10, 0x110, v195
	v_add_u32_e32 v226, s20, v12
	v_add_u32_e32 v227, s22, v12
	v_add_u32_e32 v228, s20, v11
	v_add_u32_e32 v229, s22, v11
	v_mul_u32_u24_e32 v11, 0x410, v195
	v_mad_u32_u24 v12, v195, s8, v207
	v_add_u32_e32 v15, 0x4100, v217
	v_add_u32_e32 v16, 0x8200, v217
	v_add_u32_e32 v17, 0xc300, v217
	v_add_u32_e32 v18, 0x10400, v217
	s_addc_u32 s3, s39, 0
	v_readlane_b32 s53, v249, 61
	s_movk_i32 s89, 0xff80
	v_readlane_b32 s55, v249, 60
	v_ashrrev_i32_e32 v177, 31, v176
	v_mov_b32_e32 v175, v1
	v_add_u32_e32 v182, 0x10000, v174
	v_mov_b32_e32 v183, v1
	v_add_u32_e32 v184, 0x20000, v174
	v_mov_b32_e32 v185, v1
	v_add_u32_e32 v186, 0x30000, v174
	v_mov_b32_e32 v187, v1
	v_add_u32_e32 v188, 0x40000, v174
	v_mov_b32_e32 v189, v1
	v_add_u32_e32 v190, 0x50000, v174
	v_mov_b32_e32 v191, v1
	v_add_u32_e32 v192, 0x60000, v174
	v_mov_b32_e32 v193, v1
	v_add_u32_e32 v198, 0x70000, v174
	v_mov_b32_e32 v199, v1
	v_lshl_add_u64 v[202:203], v[6:7], 2, s[2:3]
	v_add_u32_e32 v230, v13, v0
	v_add_u32_e32 v231, v13, v3
	v_add_u32_e32 v232, v13, v8
	v_add_u32_e32 v233, v13, v9
	v_add_u32_e32 v234, v14, v10
	v_add_u32_e32 v235, v2, v11
	v_add_u32_e32 v236, v2, v12
	v_add_u32_e32 v237, v216, v15
	v_add_u32_e32 v238, v216, v16
	v_add_u32_e32 v239, v216, v17
	v_add_u32_e32 v240, v216, v18
	v_readlane_b32 s19, v250, 58
	v_readlane_b32 s20, v250, 57
	v_readlane_b32 s21, v250, 0
	v_readlane_b32 s56, v249, 23
	v_readlane_b32 s62, v249, 29
	v_readlane_b32 s63, v249, 30
	v_readlane_b32 s64, v249, 31
	v_readlane_b32 s65, v249, 32
	s_waitcnt vmcnt(0)
	s_branch .LBB0_318
	s_nop 0
	s_nop 0
	s_nop 0
	s_nop 0
	s_nop 0
	s_nop 0
	s_nop 0
	s_nop 0
	s_nop 0
	s_nop 0
	s_nop 0
; #define LAS __attribute__((address_space(3)))
; __device__ __forceinline__ void phase_spatial(const Args& A, int j, LAS unsigned char* lds, int tid, int wid, int lane, bf16* ydst, unsigned ystride) {
;     ...
;         float cr[4], bi[4];
; #pragma unroll
;         for (int mb = 0; mb < 4; ++mb) { cr[mb] = corrL[mb * 32 + r32]; bi[mb] = biasL[mb * 32 + r32]; }
;         f32x4 ngv[4];
; #pragma unroll
;         for (int g4 = 0; g4 < 4; ++g4) ngv[g4] = *(const f32x4*)(ng + cw + 8 * g4 + 4 * half);
;         __syncthreads();
; #pragma unroll
;         for (int mb = 0; mb < 4; ++mb)
; #pragma unroll
;             for (int g4 = 0; g4 < 4; ++g4) { f32x4 v;
; #pragma unroll
;                 for (int e = 0; e < 4; ++e) v[e] = ngv[g4][e] * (acc[mb][4 * g4 + e] - cr[mb]) + bi[mb];
;                 *(LAS f32x4*)(tile + (mb * 32 + r32) * TST + wid * 32 + 8 * g4 + 4 * half) = v; }
;         __syncthreads();
.LBB0_317:
	ds_read_b32 v172, v222
	ds_read_b32 v242, v223
	ds_read_b32 v168, v224
	ds_read_b32 v170, v225
	ds_read_b32 v164, v226
	ds_read_b32 v166, v227
	ds_read_b32 v0, v228
	ds_read_b32 v162, v229
	s_waitcnt lgkmcnt(0)
	v_pk_add_f32 v[50:51], v[50:51], v[172:173] op_sel_hi:[1,0] neg_lo:[0,1] neg_hi:[0,1]
	v_pk_add_f32 v[52:53], v[52:53], v[172:173] op_sel_hi:[1,0] neg_lo:[0,1] neg_hi:[0,1]
	v_pk_add_f32 v[2:3], v[2:3], v[0:1] op_sel_hi:[1,0] neg_lo:[0,1] neg_hi:[0,1]
	v_pk_add_f32 v[4:5], v[4:5], v[0:1] op_sel_hi:[1,0] neg_lo:[0,1] neg_hi:[0,1]
	v_pk_add_f32 v[34:35], v[34:35], v[168:169] op_sel_hi:[1,0] neg_lo:[0,1] neg_hi:[0,1]
	v_pk_add_f32 v[36:37], v[36:37], v[168:169] op_sel_hi:[1,0] neg_lo:[0,1] neg_hi:[0,1]
	v_pk_add_f32 v[18:19], v[18:19], v[164:165] op_sel_hi:[1,0] neg_lo:[0,1] neg_hi:[0,1]
	v_pk_add_f32 v[20:21], v[20:21], v[164:165] op_sel_hi:[1,0] neg_lo:[0,1] neg_hi:[0,1]
	s_barrier
	s_add_i32 s20, s20, s53
	s_add_i32 s19, s19, s26
	s_and_b64 vcc, exec, s[2:3]
	s_waitcnt vmcnt(0)
.Lsp_after:
	v_pk_fma_f32 v[2:3], v[2:3], v[158:159], v[162:163] op_sel_hi:[1,1,0]
	v_pk_fma_f32 v[4:5], v[4:5], v[160:161], v[162:163] op_sel_hi:[1,1,0]
	v_pk_fma_f32 v[50:51], v[50:51], v[158:159], v[242:243] op_sel_hi:[1,1,0]
	v_pk_fma_f32 v[52:53], v[52:53], v[160:161], v[242:243] op_sel_hi:[1,1,0]
	v_pk_fma_f32 v[34:35], v[34:35], v[158:159], v[170:171] op_sel_hi:[1,1,0]
	v_pk_fma_f32 v[36:37], v[36:37], v[160:161], v[170:171] op_sel_hi:[1,1,0]
	v_pk_fma_f32 v[18:19], v[18:19], v[158:159], v[166:167] op_sel_hi:[1,1,0]
	v_pk_fma_f32 v[20:21], v[20:21], v[160:161], v[166:167] op_sel_hi:[1,1,0]
	ds_write_b128 v236, v[2:5] offset:33280
	v_pk_add_f32 v[2:3], v[6:7], v[0:1] op_sel_hi:[1,0] neg_lo:[0,1] neg_hi:[0,1]
	v_pk_add_f32 v[4:5], v[8:9], v[0:1] op_sel_hi:[1,0] neg_lo:[0,1] neg_hi:[0,1]
	ds_write_b128 v235, v[50:53]
	v_pk_add_f32 v[50:51], v[54:55], v[172:173] op_sel_hi:[1,0] neg_lo:[0,1] neg_hi:[0,1]
	v_pk_add_f32 v[52:53], v[56:57], v[172:173] op_sel_hi:[1,0] neg_lo:[0,1] neg_hi:[0,1]
	ds_write_b128 v235, v[34:37] offset:33280
	v_pk_add_f32 v[34:35], v[38:39], v[168:169] op_sel_hi:[1,0] neg_lo:[0,1] neg_hi:[0,1]
	v_pk_add_f32 v[36:37], v[40:41], v[168:169] op_sel_hi:[1,0] neg_lo:[0,1] neg_hi:[0,1]
	ds_write_b128 v236, v[18:21]
	v_pk_add_f32 v[18:19], v[22:23], v[164:165] op_sel_hi:[1,0] neg_lo:[0,1] neg_hi:[0,1]
	v_pk_add_f32 v[20:21], v[24:25], v[164:165] op_sel_hi:[1,0] neg_lo:[0,1] neg_hi:[0,1]
	v_pk_fma_f32 v[2:3], v[2:3], v[154:155], v[162:163] op_sel_hi:[1,1,0]
	v_pk_fma_f32 v[4:5], v[4:5], v[156:157], v[162:163] op_sel_hi:[1,1,0]
	v_pk_fma_f32 v[50:51], v[50:51], v[154:155], v[242:243] op_sel_hi:[1,1,0]
	v_pk_fma_f32 v[52:53], v[52:53], v[156:157], v[242:243] op_sel_hi:[1,1,0]
	v_pk_fma_f32 v[34:35], v[34:35], v[154:155], v[170:171] op_sel_hi:[1,1,0]
	v_pk_fma_f32 v[36:37], v[36:37], v[156:157], v[170:171] op_sel_hi:[1,1,0]
	v_pk_fma_f32 v[18:19], v[18:19], v[154:155], v[166:167] op_sel_hi:[1,1,0]
	v_pk_fma_f32 v[20:21], v[20:21], v[156:157], v[166:167] op_sel_hi:[1,1,0]
	ds_write_b128 v236, v[2:5] offset:33312
	v_pk_add_f32 v[2:3], v[10:11], v[0:1] op_sel_hi:[1,0] neg_lo:[0,1] neg_hi:[0,1]
	v_pk_add_f32 v[4:5], v[12:13], v[0:1] op_sel_hi:[1,0] neg_lo:[0,1] neg_hi:[0,1]
	ds_write_b128 v235, v[50:53] offset:32
	v_pk_add_f32 v[50:51], v[58:59], v[172:173] op_sel_hi:[1,0] neg_lo:[0,1] neg_hi:[0,1]
	v_pk_add_f32 v[52:53], v[60:61], v[172:173] op_sel_hi:[1,0] neg_lo:[0,1] neg_hi:[0,1]
	ds_write_b128 v235, v[34:37] offset:33312
	v_pk_add_f32 v[34:35], v[42:43], v[168:169] op_sel_hi:[1,0] neg_lo:[0,1] neg_hi:[0,1]
	v_pk_add_f32 v[36:37], v[44:45], v[168:169] op_sel_hi:[1,0] neg_lo:[0,1] neg_hi:[0,1]
	ds_write_b128 v236, v[18:21] offset:32
	v_pk_add_f32 v[18:19], v[26:27], v[164:165] op_sel_hi:[1,0] neg_lo:[0,1] neg_hi:[0,1]
	v_pk_add_f32 v[20:21], v[28:29], v[164:165] op_sel_hi:[1,0] neg_lo:[0,1] neg_hi:[0,1]
	v_pk_fma_f32 v[2:3], v[2:3], v[150:151], v[162:163] op_sel_hi:[1,1,0]
	v_pk_fma_f32 v[4:5], v[4:5], v[152:153], v[162:163] op_sel_hi:[1,1,0]
	v_pk_fma_f32 v[50:51], v[50:51], v[150:151], v[242:243] op_sel_hi:[1,1,0]
	v_pk_fma_f32 v[52:53], v[52:53], v[152:153], v[242:243] op_sel_hi:[1,1,0]
	v_pk_fma_f32 v[34:35], v[34:35], v[150:151], v[170:171] op_sel_hi:[1,1,0]
	v_pk_fma_f32 v[36:37], v[36:37], v[152:153], v[170:171] op_sel_hi:[1,1,0]
	v_pk_fma_f32 v[18:19], v[18:19], v[150:151], v[166:167] op_sel_hi:[1,1,0]
	v_pk_fma_f32 v[20:21], v[20:21], v[152:153], v[166:167] op_sel_hi:[1,1,0]
	ds_write_b128 v236, v[2:5] offset:33344
	v_pk_add_f32 v[2:3], v[14:15], v[0:1] op_sel_hi:[1,0] neg_lo:[0,1] neg_hi:[0,1]
	v_pk_add_f32 v[4:5], v[16:17], v[0:1] op_sel_hi:[1,0] neg_lo:[0,1] neg_hi:[0,1]
	ds_write_b128 v235, v[50:53] offset:64
	v_pk_add_f32 v[50:51], v[62:63], v[172:173] op_sel_hi:[1,0] neg_lo:[0,1] neg_hi:[0,1]
	v_pk_add_f32 v[52:53], v[64:65], v[172:173] op_sel_hi:[1,0] neg_lo:[0,1] neg_hi:[0,1]
	ds_write_b128 v235, v[34:37] offset:33344
	v_pk_add_f32 v[34:35], v[46:47], v[168:169] op_sel_hi:[1,0] neg_lo:[0,1] neg_hi:[0,1]
	v_pk_add_f32 v[36:37], v[48:49], v[168:169] op_sel_hi:[1,0] neg_lo:[0,1] neg_hi:[0,1]
	ds_write_b128 v236, v[18:21] offset:64
	v_pk_add_f32 v[18:19], v[30:31], v[164:165] op_sel_hi:[1,0] neg_lo:[0,1] neg_hi:[0,1]
	v_pk_add_f32 v[20:21], v[32:33], v[164:165] op_sel_hi:[1,0] neg_lo:[0,1] neg_hi:[0,1]
	v_pk_fma_f32 v[2:3], v[2:3], v[146:147], v[162:163] op_sel_hi:[1,1,0]
	v_pk_fma_f32 v[4:5], v[4:5], v[148:149], v[162:163] op_sel_hi:[1,1,0]
	v_lshlrev_b32_e32 v0, 1, v241
	v_pk_fma_f32 v[50:51], v[50:51], v[146:147], v[242:243] op_sel_hi:[1,1,0]
	v_pk_fma_f32 v[52:53], v[52:53], v[148:149], v[242:243] op_sel_hi:[1,1,0]
	v_pk_fma_f32 v[34:35], v[34:35], v[146:147], v[170:171] op_sel_hi:[1,1,0]
	v_pk_fma_f32 v[36:37], v[36:37], v[148:149], v[170:171] op_sel_hi:[1,1,0]
	v_pk_fma_f32 v[18:19], v[18:19], v[146:147], v[166:167] op_sel_hi:[1,1,0]
	v_pk_fma_f32 v[20:21], v[20:21], v[148:149], v[166:167] op_sel_hi:[1,1,0]
	ds_write_b128 v236, v[2:5] offset:33376
	v_lshl_add_u64 v[2:3], s[8:9], 0, v[0:1]
	v_add_u32_e32 v0, v216, v217
	ds_write_b128 v235, v[50:53] offset:96
	ds_write_b128 v235, v[34:37] offset:33376
	ds_write_b128 v236, v[18:21] offset:96
	s_waitcnt lgkmcnt(0)
	s_barrier
; #define LAS __attribute__((address_space(3)))
; __device__ __forceinline__ unsigned pk2(float lo, float hi) { f32x2 v = {lo, hi}; bf16x2_t b = __builtin_convertvector(v, bf16x2_t); return __builtin_bit_cast(unsigned, b); }
; __device__ __forceinline__ void phase_spatial(const Args& A, int j, LAS unsigned char* lds, int tid, int wid, int lane, bf16* ydst, unsigned ystride) {
;     ...
;         bf16* yb = ydst + (size_t)t0 * ystride + (unsigned)(g * GD + (tid & 31) * 8);
; #pragma unroll
;         for (int k = 0; k < 8; ++k) { const int t = (tid >> 5) + 16 * k; const LAS f32x4* tp = (const LAS f32x4*)(tile + t * TST + (tid & 31) * 8); const f32x4 v0 = tp[0], v1 = tp[1];
;             u32x4 o;
;             o.x = pk2(bf_lo(uv[k].x) * v0[0], bf_hi(uv[k].x) * v0[1]);
;             o.y = pk2(bf_lo(uv[k].y) * v0[2], bf_hi(uv[k].y) * v0[3]);
;             o.z = pk2(bf_lo(uv[k].z) * v1[0], bf_hi(uv[k].z) * v1[1]);
;             o.w = pk2(bf_lo(uv[k].w) * v1[2], bf_hi(uv[k].w) * v1[3]);
;             *(u32x4*)(yb + (unsigned)t * ystride) = o; }
;         __syncthreads();
	ds_read_b128 v[4:7], v0
	ds_read_b128 v[8:11], v0 offset:16
	v_lshlrev_b32_e32 v12, 16, v142
	v_and_b32_e32 v13, 0xffff0000, v142
	s_waitcnt lgkmcnt(1)
	v_pk_mul_f32 v[4:5], v[4:5], v[12:13]
	v_lshlrev_b32_e32 v12, 16, v143
	v_and_b32_e32 v13, 0xffff0000, v143
	v_pk_mul_f32 v[6:7], v[6:7], v[12:13]
	v_cvt_pk_bf16_f32 v4, v4, v5
	v_cvt_pk_bf16_f32 v5, v6, v7
	v_lshlrev_b32_e32 v6, 16, v144
	v_and_b32_e32 v7, 0xffff0000, v144
	s_waitcnt lgkmcnt(0)
	v_pk_mul_f32 v[6:7], v[8:9], v[6:7]
	v_lshlrev_b32_e32 v8, 16, v145
	v_and_b32_e32 v9, 0xffff0000, v145
	v_pk_mul_f32 v[8:9], v[10:11], v[8:9]
	v_cvt_pk_bf16_f32 v6, v6, v7
	v_cvt_pk_bf16_f32 v7, v8, v9
	v_lshl_add_u64 v[8:9], v[174:175], 1, v[2:3]
	flat_store_dwordx4 v[8:9], v[4:7]
	ds_read_b128 v[4:7], v237
	ds_read_b128 v[8:11], v237 offset:16
	v_lshlrev_b32_e32 v12, 16, v138
	v_and_b32_e32 v13, 0xffff0000, v138
	s_waitcnt lgkmcnt(0)
	v_pk_mul_f32 v[4:5], v[4:5], v[12:13]
	v_lshlrev_b32_e32 v12, 16, v139
	v_and_b32_e32 v13, 0xffff0000, v139
	v_pk_mul_f32 v[6:7], v[6:7], v[12:13]
	v_cvt_pk_bf16_f32 v4, v4, v5
	v_cvt_pk_bf16_f32 v5, v6, v7
	v_lshlrev_b32_e32 v6, 16, v140
	v_and_b32_e32 v7, 0xffff0000, v140
	v_pk_mul_f32 v[6:7], v[8:9], v[6:7]
	v_lshlrev_b32_e32 v8, 16, v141
	v_and_b32_e32 v9, 0xffff0000, v141
	v_pk_mul_f32 v[8:9], v[10:11], v[8:9]
	v_cvt_pk_bf16_f32 v6, v6, v7
	v_cvt_pk_bf16_f32 v7, v8, v9
	v_lshl_add_u64 v[8:9], v[182:183], 1, v[2:3]
	flat_store_dwordx4 v[8:9], v[4:7]
	ds_read_b128 v[4:7], v237 offset:16640
	ds_read_b128 v[8:11], v237 offset:16656
	v_lshlrev_b32_e32 v12, 16, v134
	v_and_b32_e32 v13, 0xffff0000, v134
	s_waitcnt lgkmcnt(0)
	v_pk_mul_f32 v[4:5], v[4:5], v[12:13]
	v_lshlrev_b32_e32 v12, 16, v135
	v_and_b32_e32 v13, 0xffff0000, v135
	v_pk_mul_f32 v[6:7], v[6:7], v[12:13]
	v_cvt_pk_bf16_f32 v4, v4, v5
	v_cvt_pk_bf16_f32 v5, v6, v7
	v_lshlrev_b32_e32 v6, 16, v136
	v_and_b32_e32 v7, 0xffff0000, v136
	v_pk_mul_f32 v[6:7], v[8:9], v[6:7]
	v_lshlrev_b32_e32 v8, 16, v137
	v_and_b32_e32 v9, 0xffff0000, v137
	v_pk_mul_f32 v[8:9], v[10:11], v[8:9]
	v_cvt_pk_bf16_f32 v6, v6, v7
	v_cvt_pk_bf16_f32 v7, v8, v9
	v_lshl_add_u64 v[8:9], v[184:185], 1, v[2:3]
	flat_store_dwordx4 v[8:9], v[4:7]
	ds_read_b128 v[4:7], v237 offset:33280
	ds_read_b128 v[8:11], v237 offset:33296
	v_lshlrev_b32_e32 v12, 16, v130
	v_and_b32_e32 v13, 0xffff0000, v130
	s_waitcnt lgkmcnt(0)
	v_pk_mul_f32 v[4:5], v[4:5], v[12:13]
	v_lshlrev_b32_e32 v12, 16, v131
	v_and_b32_e32 v13, 0xffff0000, v131
	v_pk_mul_f32 v[6:7], v[6:7], v[12:13]
	v_cvt_pk_bf16_f32 v4, v4, v5
	v_cvt_pk_bf16_f32 v5, v6, v7
	v_lshlrev_b32_e32 v6, 16, v132
	v_and_b32_e32 v7, 0xffff0000, v132
	v_pk_mul_f32 v[6:7], v[8:9], v[6:7]
	v_lshlrev_b32_e32 v8, 16, v133
	v_and_b32_e32 v9, 0xffff0000, v133
	v_pk_mul_f32 v[8:9], v[10:11], v[8:9]
	v_cvt_pk_bf16_f32 v6, v6, v7
	v_cvt_pk_bf16_f32 v7, v8, v9
	v_lshl_add_u64 v[8:9], v[186:187], 1, v[2:3]
	flat_store_dwordx4 v[8:9], v[4:7]
	ds_read_b128 v[4:7], v237 offset:49920
	ds_read_b128 v[8:11], v237 offset:49936
	v_lshlrev_b32_e32 v12, 16, v126
	v_and_b32_e32 v13, 0xffff0000, v126
	s_waitcnt lgkmcnt(0)
	v_pk_mul_f32 v[4:5], v[4:5], v[12:13]
	v_lshlrev_b32_e32 v12, 16, v127
	v_and_b32_e32 v13, 0xffff0000, v127
	v_pk_mul_f32 v[6:7], v[6:7], v[12:13]
	v_cvt_pk_bf16_f32 v4, v4, v5
	v_cvt_pk_bf16_f32 v5, v6, v7
	v_lshlrev_b32_e32 v6, 16, v128
	v_and_b32_e32 v7, 0xffff0000, v128
	v_pk_mul_f32 v[6:7], v[8:9], v[6:7]
	v_lshlrev_b32_e32 v8, 16, v129
	v_and_b32_e32 v9, 0xffff0000, v129
	v_pk_mul_f32 v[8:9], v[10:11], v[8:9]
	v_cvt_pk_bf16_f32 v6, v6, v7
	v_cvt_pk_bf16_f32 v7, v8, v9
	v_lshl_add_u64 v[8:9], v[188:189], 1, v[2:3]
	flat_store_dwordx4 v[8:9], v[4:7]
	ds_read_b128 v[4:7], v238 offset:49920
	ds_read_b128 v[8:11], v238 offset:49936
	v_lshlrev_b32_e32 v12, 16, v122
	v_and_b32_e32 v13, 0xffff0000, v122
	s_waitcnt lgkmcnt(0)
	v_pk_mul_f32 v[4:5], v[4:5], v[12:13]
	v_lshlrev_b32_e32 v12, 16, v123
	v_and_b32_e32 v13, 0xffff0000, v123
	v_pk_mul_f32 v[6:7], v[6:7], v[12:13]
	v_cvt_pk_bf16_f32 v4, v4, v5
	v_cvt_pk_bf16_f32 v5, v6, v7
	v_lshlrev_b32_e32 v6, 16, v124
	v_and_b32_e32 v7, 0xffff0000, v124
	v_pk_mul_f32 v[6:7], v[8:9], v[6:7]
	v_lshlrev_b32_e32 v8, 16, v125
	v_and_b32_e32 v9, 0xffff0000, v125
	v_pk_mul_f32 v[8:9], v[10:11], v[8:9]
	v_cvt_pk_bf16_f32 v6, v6, v7
	v_cvt_pk_bf16_f32 v7, v8, v9
	v_lshl_add_u64 v[8:9], v[190:191], 1, v[2:3]
	flat_store_dwordx4 v[8:9], v[4:7]
	ds_read_b128 v[4:7], v239 offset:49920
	ds_read_b128 v[8:11], v239 offset:49936
	v_lshlrev_b32_e32 v12, 16, v118
	v_and_b32_e32 v13, 0xffff0000, v118
	s_waitcnt lgkmcnt(0)
	v_pk_mul_f32 v[4:5], v[4:5], v[12:13]
	v_lshlrev_b32_e32 v12, 16, v119
	v_and_b32_e32 v13, 0xffff0000, v119
	v_pk_mul_f32 v[6:7], v[6:7], v[12:13]
	v_cvt_pk_bf16_f32 v4, v4, v5
	v_cvt_pk_bf16_f32 v5, v6, v7
	v_lshlrev_b32_e32 v6, 16, v120
	v_and_b32_e32 v7, 0xffff0000, v120
	v_pk_mul_f32 v[6:7], v[8:9], v[6:7]
	v_lshlrev_b32_e32 v8, 16, v121
	v_and_b32_e32 v9, 0xffff0000, v121
	v_pk_mul_f32 v[8:9], v[10:11], v[8:9]
	v_cvt_pk_bf16_f32 v6, v6, v7
	v_cvt_pk_bf16_f32 v7, v8, v9
	v_lshl_add_u64 v[8:9], v[192:193], 1, v[2:3]
	flat_store_dwordx4 v[8:9], v[4:7]
	ds_read_b128 v[4:7], v240 offset:49920
	ds_read_b128 v[8:11], v240 offset:49936
	v_lshlrev_b32_e32 v12, 16, v114
	v_and_b32_e32 v13, 0xffff0000, v114
	v_lshl_add_u64 v[2:3], v[198:199], 1, v[2:3]
	s_waitcnt lgkmcnt(0)
	v_pk_mul_f32 v[4:5], v[4:5], v[12:13]
	v_lshlrev_b32_e32 v12, 16, v115
	v_and_b32_e32 v13, 0xffff0000, v115
	v_pk_mul_f32 v[6:7], v[6:7], v[12:13]
	v_cvt_pk_bf16_f32 v4, v4, v5
	v_cvt_pk_bf16_f32 v5, v6, v7
	v_lshlrev_b32_e32 v6, 16, v116
	v_and_b32_e32 v7, 0xffff0000, v116
	v_pk_mul_f32 v[6:7], v[8:9], v[6:7]
	v_lshlrev_b32_e32 v8, 16, v117
	v_and_b32_e32 v9, 0xffff0000, v117
	v_pk_mul_f32 v[8:9], v[10:11], v[8:9]
	v_cvt_pk_bf16_f32 v6, v6, v7
	v_cvt_pk_bf16_f32 v7, v8, v9
	flat_store_dwordx4 v[2:3], v[4:7]
	s_waitcnt lgkmcnt(0)
	s_barrier
	s_cbranch_vccnz .LBB0_324
; __device__ __forceinline__ void phase_spatial(const Args& A, int j, LAS unsigned char* lds, int tid, int wid, int lane, bf16* ydst, unsigned ystride) {
;     ...
;     for (int unit = blockIdx.x; unit < (MTOK / SBLK) * NG; unit += gridDim.x) {
;         const int g = unit & 15, nblk = unit >> 4, t0 = nblk * SBLK;
;         const unsigned uoff = (unsigned)(tid >> 5) * EW + (unsigned)(g * GD + (tid & 31) * 8);
;         const bf16* ub = UZ + (size_t)t0 * EW;
;         u32x4 uv[8];
; #pragma unroll
;         for (int k = 0; k < 8; ++k) uv[k] = *(const u32x4*)(ub + uoff + (unsigned)k * 16 * EW);
;         { const int t = tid >> 2, p = tid & 3; float s = 0.f, q = 0.f;
; #pragma unroll
;           for (int k = 0; k < 8; ++k) { const f32x2 v = stv[k]; s += v.x; q += v.y; }
;           s += shx<1>(s); q += shx<1>(q); s += shx<2>(s); q += shx<2>(q);
;           const float mu = s * (1.0f / EW), var = q * (1.0f / EW) - mu * mu;
;           if (p == 0) { muL[t] = mu; rsL[t] = __builtin_amdgcn_rsqf(fmaxf(var, 0.f) + EPS); } }
.LBB0_318:
	s_ashr_i32 s2, s21, 4
	s_lshl_b32 s8, s2, 7
	s_and_b32 s22, s21, 15
	s_ashr_i32 s9, s8, 31
	s_lshl_b32 s3, s22, 8
	s_lshl_b64 s[8:9], s[8:9], 13
	v_or_b32_e32 v241, s3, v197
	s_add_u32 s8, s6, s8
	v_or_b32_e32 v0, v241, v174
	s_addc_u32 s9, s7, s9
	v_lshl_add_u64 v[2:3], v[0:1], 1, s[8:9]
	s_mov_b32 s12, 0x20000
	v_add_co_u32_e32 v4, vcc, s12, v2
	s_mov_b32 s12, 0x40000
	s_nop 0
	v_addc_co_u32_e32 v5, vcc, 0, v3, vcc
	s_waitcnt vmcnt(8)
	flat_load_dwordx4 v[142:145], v[2:3]
	flat_load_dwordx4 v[138:141], v[4:5]
	v_add_co_u32_e32 v4, vcc, s12, v2
	s_mov_b32 s12, 0x60000
	s_nop 0
	v_addc_co_u32_e32 v5, vcc, 0, v3, vcc
	flat_load_dwordx4 v[134:137], v[4:5]
	v_add_co_u32_e32 v4, vcc, s12, v2
	s_mov_b32 s12, 0x80000
	s_nop 0
	v_addc_co_u32_e32 v5, vcc, 0, v3, vcc
	flat_load_dwordx4 v[130:133], v[4:5]
	v_add_co_u32_e32 v4, vcc, s12, v2
	s_mov_b32 s12, 0xa0000
	s_nop 0
	v_addc_co_u32_e32 v5, vcc, 0, v3, vcc
	flat_load_dwordx4 v[126:129], v[4:5]
	v_add_co_u32_e32 v4, vcc, s12, v2
	s_mov_b32 s12, 0xc0000
	s_nop 0
	v_addc_co_u32_e32 v5, vcc, 0, v3, vcc
	flat_load_dwordx4 v[122:125], v[4:5]
	v_add_co_u32_e32 v4, vcc, s12, v2
	s_mov_b32 s12, 0xe0000
	s_nop 0
	v_addc_co_u32_e32 v5, vcc, 0, v3, vcc
	v_add_co_u32_e32 v2, vcc, s12, v2
	flat_load_dwordx4 v[118:121], v[4:5]
	s_nop 0
	v_addc_co_u32_e32 v3, vcc, 0, v3, vcc
	flat_load_dwordx4 v[114:117], v[2:3]
	s_waitcnt lgkmcnt(0)
	v_add_f32_e32 v0, 0, v66
	v_add_f32_e32 v0, v0, v68
	v_add_f32_e32 v0, v0, v70
	v_add_f32_e32 v0, v0, v72
	v_add_f32_e32 v0, v0, v74
	v_add_f32_e32 v2, 0, v67
	v_add_f32_e32 v0, v0, v76
	v_add_f32_e32 v2, v2, v69
	v_add_f32_e32 v0, v0, v78
	v_add_f32_e32 v2, v2, v71
	v_add_f32_e32 v0, v0, v80
	v_add_f32_e32 v2, v2, v73
	ds_swizzle_b32 v3, v0 offset:swizzle(SWAP,1)
	v_add_f32_e32 v2, v2, v75
	v_add_f32_e32 v2, v2, v77
	v_add_f32_e32 v2, v2, v79
	v_add_f32_e32 v2, v2, v81
	s_waitcnt lgkmcnt(0)
	v_add_f32_e32 v0, v0, v3
	ds_swizzle_b32 v3, v2 offset:swizzle(SWAP,1)
	s_waitcnt lgkmcnt(0)
	v_add_f32_e32 v2, v2, v3
	ds_swizzle_b32 v3, v0 offset:swizzle(SWAP,2)
	ds_swizzle_b32 v4, v2 offset:swizzle(SWAP,2)
	s_and_saveexec_b64 s[12:13], s[0:1]
	s_cbranch_execz .LBB0_320
	s_waitcnt lgkmcnt(0)
	v_add_f32_e32 v0, v0, v3
	v_mul_f32_e32 v0, 0x39800000, v0
	v_add_f32_e32 v2, v2, v4
	v_mul_f32_e32 v3, v0, v0
	s_mov_b32 s23, 0x39800000
	v_fma_f32 v2, v2, s23, -v3
	v_max_f32_e32 v2, 0, v2
	v_add_f32_e32 v2, 0x358637bd, v2
	v_rsq_f32_e32 v2, v2
	ds_write_b32 v211, v0
	ds_write_b32 v212, v2

; #define LAS __attribute__((address_space(3)))
; __device__ __forceinline__ void phase_spatial(const Args& A, int j, LAS unsigned char* lds, int tid, int wid, int lane, bf16* ydst, unsigned ystride) {
;     ...
;         f32x16 acc[4];
; #pragma unroll
;         for (int mb = 0; mb < 4; ++mb) {
; #pragma unroll
;             for (int i = 0; i < 16; ++i) acc[mb][i] = 0.f;
; #pragma unroll
;             for (int ks = 0; ks < 8; ++ks) { if (mb < 2 && ks >= 4) continue;
;                 const bf16x8 af = *(const LAS bf16x8*)(Aimg + (mb * 32 + r32) * AST + ks * 32 + half * 16);
;                 acc[mb] = __builtin_amdgcn_mfma_f32_32x32x16_bf16(gfr[ks], af, acc[mb], 0, 0, 0); }
;             __builtin_amdgcn_sched_barrier(0); }
;         if (unit + (int)gridDim.x < (MTOK / SBLK) * NG) SP_PREFETCH(unit + (int)gridDim.x);
;         float cr[4], bi[4];
; #pragma unroll
;         for (int mb = 0; mb < 4; ++mb) { cr[mb] = corrL[mb * 32 + r32]; bi[mb] = biasL[mb * 32 + r32]; }
;         f32x4 ngv[4];
; #pragma unroll
;         for (int g4 = 0; g4 < 4; ++g4) ngv[g4] = *(const f32x4*)(ng + cw + 8 * g4 + 4 * half);
;         __syncthreads();
.LBB0_322:
	s_or_b64 exec, exec, s[2:3]
	s_waitcnt lgkmcnt(0)
	s_barrier
	ds_read_b128 v[6:9], v234
	s_waitcnt vmcnt(0) lgkmcnt(0)
	v_mfma_f32_32x32x16_bf16 v[50:65], v[2:5], v[6:9], 0
	ds_read_b128 v[6:9], v234 offset:32
	s_waitcnt lgkmcnt(0)
	v_mfma_f32_32x32x16_bf16 v[50:65], v[170:173], v[6:9], v[50:65]
	ds_read_b128 v[6:9], v234 offset:64
	s_waitcnt lgkmcnt(0)
	v_mfma_f32_32x32x16_bf16 v[50:65], v[166:169], v[6:9], v[50:65]
	ds_read_b128 v[6:9], v234 offset:96
	s_waitcnt lgkmcnt(0)
	v_mfma_f32_32x32x16_bf16 v[50:65], v[162:165], v[6:9], v[50:65]
	ds_read_b128 v[6:9], v234 offset:8704
	s_waitcnt lgkmcnt(0)
	v_mfma_f32_32x32x16_bf16 v[34:49], v[2:5], v[6:9], 0
	ds_read_b128 v[6:9], v234 offset:8736
	s_waitcnt lgkmcnt(0)
	v_mfma_f32_32x32x16_bf16 v[34:49], v[170:173], v[6:9], v[34:49]
	ds_read_b128 v[6:9], v234 offset:8768
	s_waitcnt lgkmcnt(0)
	v_mfma_f32_32x32x16_bf16 v[34:49], v[166:169], v[6:9], v[34:49]
	ds_read_b128 v[6:9], v234 offset:8800
	s_waitcnt lgkmcnt(0)
	v_mfma_f32_32x32x16_bf16 v[34:49], v[162:165], v[6:9], v[34:49]
	ds_read_b128 v[6:9], v234 offset:17408
	s_waitcnt lgkmcnt(0)
	v_mfma_f32_32x32x16_bf16 v[18:33], v[2:5], v[6:9], 0
	ds_read_b128 v[6:9], v234 offset:17440
	s_waitcnt lgkmcnt(0)
	v_mfma_f32_32x32x16_bf16 v[18:33], v[170:173], v[6:9], v[18:33]
	ds_read_b128 v[6:9], v234 offset:17472
	s_waitcnt lgkmcnt(0)
	v_mfma_f32_32x32x16_bf16 v[18:33], v[166:169], v[6:9], v[18:33]
	ds_read_b128 v[6:9], v234 offset:17504
	s_waitcnt lgkmcnt(0)
	v_mfma_f32_32x32x16_bf16 v[18:33], v[162:165], v[6:9], v[18:33]
	ds_read_b128 v[6:9], v234 offset:17536
	s_waitcnt lgkmcnt(0)
	v_mfma_f32_32x32x16_bf16 v[18:33], v[158:161], v[6:9], v[18:33]
	ds_read_b128 v[6:9], v234 offset:17568
	s_waitcnt lgkmcnt(0)
	v_mfma_f32_32x32x16_bf16 v[18:33], v[154:157], v[6:9], v[18:33]
	ds_read_b128 v[6:9], v234 offset:17600
	s_waitcnt lgkmcnt(0)
	v_mfma_f32_32x32x16_bf16 v[18:33], v[150:153], v[6:9], v[18:33]
	ds_read_b128 v[6:9], v234 offset:17632
	s_waitcnt lgkmcnt(0)
	v_mfma_f32_32x32x16_bf16 v[18:33], v[146:149], v[6:9], v[18:33]
	ds_read_b128 v[6:9], v234 offset:26112
	ds_read_b128 v[242:245], v234 offset:26144
	s_waitcnt lgkmcnt(1)
	v_mfma_f32_32x32x16_bf16 v[2:17], v[2:5], v[6:9], 0
	s_waitcnt lgkmcnt(0)
	v_mfma_f32_32x32x16_bf16 v[2:17], v[170:173], v[242:245], v[2:17]
	ds_read_b128 v[170:173], v234 offset:26176
	s_waitcnt lgkmcnt(0)
	v_mfma_f32_32x32x16_bf16 v[2:17], v[166:169], v[170:173], v[2:17]
	ds_read_b128 v[166:169], v234 offset:26208
	s_waitcnt lgkmcnt(0)
	v_mfma_f32_32x32x16_bf16 v[2:17], v[162:165], v[166:169], v[2:17]
	ds_read_b128 v[162:165], v234 offset:26240
	s_waitcnt lgkmcnt(0)
	v_mfma_f32_32x32x16_bf16 v[2:17], v[158:161], v[162:165], v[2:17]
	ds_read_b128 v[158:161], v234 offset:26272
	s_waitcnt lgkmcnt(0)
	v_mfma_f32_32x32x16_bf16 v[2:17], v[154:157], v[158:161], v[2:17]
	ds_read_b128 v[154:157], v234 offset:26304
	s_waitcnt lgkmcnt(0)
	v_mfma_f32_32x32x16_bf16 v[2:17], v[150:153], v[154:157], v[2:17]
	ds_read_b128 v[150:153], v234 offset:26336
	s_waitcnt lgkmcnt(0)
	v_mfma_f32_32x32x16_bf16 v[2:17], v[146:149], v[150:153], v[2:17]
	s_ashr_i32 s13, s12, 31
	v_lshl_add_u64 v[146:147], s[12:13], 2, v[180:181]
	global_load_dwordx4 v[158:161], v[146:147], off
	global_load_dwordx4 v[154:157], v[146:147], off offset:32
	global_load_dwordx4 v[150:153], v[146:147], off offset:64
	s_nop 0
	global_load_dwordx4 v[146:149], v[146:147], off offset:96
	s_add_i32 s21, s21, s86
	s_cmpk_gt_i32 s21, 0xfff
	s_cselect_b64 s[2:3], -1, 0
	s_and_b64 vcc, exec, s[2:3]
	s_cbranch_vccnz .LBB0_317
	s_and_b32 s22, s20, 0xffffff80
	s_ashr_i32 s23, s22, 31
	s_and_b32 s13, s19, 0x3c000
	s_lshl_b64 s[22:23], s[22:23], 8
	s_lshl_b32 s94, s13, 2
	v_lshl_add_u64 v[78:79], v[178:179], 0, s[22:23]
	v_lshl_add_u64 v[110:111], v[200:201], 0, s[94:95]
	flat_load_dwordx4 v[66:69], v[78:79]
	flat_load_dwordx4 v[70:73], v[78:79] offset:16
	flat_load_dwordx4 v[74:77], v[78:79] offset:32
	s_nop 0
	flat_load_dwordx4 v[78:81], v[78:79] offset:48
	s_nop 0
	global_load_dwordx4 v[82:85], v[110:111], off offset:48
	global_load_dwordx4 v[86:89], v[110:111], off offset:32
	global_load_dwordx4 v[90:93], v[110:111], off offset:16
	global_load_dwordx4 v[94:97], v[110:111], off
	global_load_dwordx4 v[98:101], v[110:111], off offset:112
	global_load_dwordx4 v[102:105], v[110:111], off offset:96
	global_load_dwordx4 v[106:109], v[110:111], off offset:80
	s_nop 0
	global_load_dwordx4 v[110:113], v[110:111], off offset:64
	ds_read_b32 v172, v222
	ds_read_b32 v242, v223
	ds_read_b32 v168, v224
	ds_read_b32 v170, v225
	ds_read_b32 v164, v226
	ds_read_b32 v166, v227
	ds_read_b32 v0, v228
	ds_read_b32 v162, v229
	s_waitcnt lgkmcnt(0)
	v_pk_add_f32 v[50:51], v[50:51], v[172:173] op_sel_hi:[1,0] neg_lo:[0,1] neg_hi:[0,1]
	v_pk_add_f32 v[52:53], v[52:53], v[172:173] op_sel_hi:[1,0] neg_lo:[0,1] neg_hi:[0,1]
	v_pk_add_f32 v[2:3], v[2:3], v[0:1] op_sel_hi:[1,0] neg_lo:[0,1] neg_hi:[0,1]
	v_pk_add_f32 v[4:5], v[4:5], v[0:1] op_sel_hi:[1,0] neg_lo:[0,1] neg_hi:[0,1]
	v_pk_add_f32 v[34:35], v[34:35], v[168:169] op_sel_hi:[1,0] neg_lo:[0,1] neg_hi:[0,1]
	v_pk_add_f32 v[36:37], v[36:37], v[168:169] op_sel_hi:[1,0] neg_lo:[0,1] neg_hi:[0,1]
	v_pk_add_f32 v[18:19], v[18:19], v[164:165] op_sel_hi:[1,0] neg_lo:[0,1] neg_hi:[0,1]
	v_pk_add_f32 v[20:21], v[20:21], v[164:165] op_sel_hi:[1,0] neg_lo:[0,1] neg_hi:[0,1]
	s_barrier
	s_add_i32 s20, s20, s53
	s_add_i32 s19, s19, s26
	s_and_b64 vcc, exec, s[2:3]
	s_waitcnt vmcnt(12)
	s_branch .Lsp_after

; __global__ void __launch_bounds__(NTHREADS, 2) fwd_kernel(Args A_) {
;     ...
;                 } else if (k == 1) { if (PHMASK & 16) {
;     ...
;                     if (li == 0) { phase_spatial(A, j, lds, tid, wid, lane, (bf16*)A.out, EW); xcd_barrier(xbar, wid0 == 0); }
;     ...
;                     phase_spatial(A, j, lds, tid, wid, lane, (bf16*)(ws + WS_UZ), EW); } }
.LBB0_325:
	s_branch .LBB0_312
	s_nop 0
	s_nop 0
	s_nop 0
	s_nop 0
	s_nop 0
	s_nop 0
	s_nop 0
	s_nop 0
	s_nop 0
	s_nop 0
	s_nop 0
	s_nop 0
	s_nop 0
	s_nop 0
